# top-k threshold search: cross-wave count reduction through LDS atomics (one ds_read + ballot popcount per step instead of 16 ds_read_b128 + ~90 VALU)
# baseline (speedup 1.0000x reference)
.LBB0_609:
	s_or_b64 exec, exec, s[4:5]
	s_mov_b32 s38, 0
	v_cmp_eq_u32_e64 s[4:5], 0, v47
	s_mov_b64 s[20:21], 0
	s_mov_b32 s28, 0
	v_lshlrev_b32_e32 v10, 2, v47
	v_mov_b32_e32 v11, 0
	ds_write_b32 v10, v11 offset:1024
	ds_write_b32 v10, v11 offset:1280
	s_waitcnt lgkmcnt(0)
	s_barrier
	s_branch .LBB0_611
.LBB0_610:
	s_add_i32 s28, s28, 1
	s_xor_b64 s[20:21], s[20:21], -1
	s_cmp_eq_u32 s28, 11
	s_cbranch_scc1 .LBB0_617

.Ltk_w5:
	s_lshl_b32 s6, s28, 5
	s_addk_i32 s6, 0x400
	v_lshl_add_u32 v10, v47, 2, s6
	s_mov_b64 s[26:27], exec
	s_mov_b64 exec, 0x7f
	ds_add_u32 v10, v11
	s_mov_b64 exec, s[26:27]
.LBB0_615:
	s_waitcnt lgkmcnt(0)
	s_barrier
	ds_read_b32 v10, v10
	s_and_b64 s[6:7], s[24:25], exec
	s_cselect_b32 s7, 0x7f, 1
	s_waitcnt lgkmcnt(0)
	v_cmp_lt_i32_e32 vcc, 31, v10
	s_and_b32 s6, vcc_lo, s7
	s_bcnt1_i32_b32 s6, s6
	s_lshl_b32 s6, s6, s29
	s_or_b32 s38, s38, s6
	s_branch .LBB0_610

.LBB0_661:
	s_waitcnt lgkmcnt(0)
	s_barrier
	ds_read_b32 v10, v10
	s_and_b64 s[6:7], s[24:25], exec
	s_cselect_b32 s7, 0x7f, 1
	s_waitcnt lgkmcnt(0)
	v_cmp_lt_i32_e32 vcc, s41, v10
	s_and_b32 s6, vcc_lo, s7
	s_bcnt1_i32_b32 s6, s6
	s_lshl_b32 s6, s6, s29
	s_or_b32 s38, s38, s6
	s_branch .LBB0_656
